# remove the in-proj GEMM phase's half-grid start stagger (s_sleep) on top of v56
# speedup vs baseline: 1.0016x; 1.0016x over previous
.LBB0_968:
	s_andn2_b64 vcc, exec, s[4:5]
	s_cbranch_vccnz .LBB0_1075
	v_readlane_b32 s4, v255, 18
	s_bitcmp0_b32 s4, 3
	v_readlane_b32 s5, v255, 19
	s_cbranch_scc1 .LBB0_971
	s_nop 0
